# code prefetch issued by one workgroup in eight (4 per XCD)
# speedup vs baseline: 1.0089x; 1.0029x over previous
_Z12trunk_kernel2KP:
	s_and_b32 s18, s2, 56
	s_cmp_lg_u32 s18, 0
	s_cbranch_scc1 .Lent_nopf
	s_getpc_b64 s[18:19]
	v_and_b32_e32 v254, 0x3ff, v0
	v_lshlrev_b32_e32 v254, 6, v254
	global_load_dword v255, v254, s[18:19]

.Lxb_pf_0:
	v_readlane_b32 s18, v252, 5
	s_nop 3
	s_and_b32 s18, s18, 56
	s_cmp_lg_u32 s18, 0
	s_cbranch_scc1 .Lxb_wait_0
	s_getpc_b64 s[18:19]
	s_mov_b64 s[22:23], exec
	s_mov_b64 exec, -1
	v_mbcnt_lo_u32_b32 v254, -1, 0
	v_mbcnt_hi_u32_b32 v254, -1, v254
	v_lshlrev_b32_e32 v254, 7, v254
	global_load_dword v255, v254, s[18:19]
	s_add_u32 s18, s18, 0x2000
	s_addc_u32 s19, s19, 0
	global_load_dword v255, v254, s[18:19]
	s_add_u32 s18, s18, 0x2000
	s_addc_u32 s19, s19, 0
	global_load_dword v255, v254, s[18:19]
	s_add_u32 s18, s18, 0x2000
	s_addc_u32 s19, s19, 0
	global_load_dword v255, v254, s[18:19]
	s_mov_b64 exec, s[22:23]

.Lxb_pf_12:
	v_readlane_b32 s18, v252, 5
	s_nop 3
	s_and_b32 s18, s18, 56
	s_cmp_lg_u32 s18, 0
	s_cbranch_scc1 .Lxb_wait_12
	s_getpc_b64 s[18:19]
	s_mov_b64 s[22:23], exec
	s_mov_b64 exec, -1
	v_mbcnt_lo_u32_b32 v254, -1, 0
	v_mbcnt_hi_u32_b32 v254, -1, v254
	v_lshlrev_b32_e32 v254, 7, v254
	global_load_dword v255, v254, s[18:19]
	s_add_u32 s18, s18, 0x2000
	s_addc_u32 s19, s19, 0
	global_load_dword v255, v254, s[18:19]
	s_add_u32 s18, s18, 0x2000
	s_addc_u32 s19, s19, 0
	global_load_dword v255, v254, s[18:19]
	s_mov_b64 exec, s[22:23]

.Lxb_pf_13:
	v_readlane_b32 s18, v252, 5
	s_nop 3
	s_and_b32 s18, s18, 56
	s_cmp_lg_u32 s18, 0
	s_cbranch_scc1 .Lxb_wait_13
	s_getpc_b64 s[18:19]
	s_mov_b64 s[22:23], exec
	s_mov_b64 exec, -1
	v_mbcnt_lo_u32_b32 v254, -1, 0
	v_mbcnt_hi_u32_b32 v254, -1, v254
	v_lshlrev_b32_e32 v254, 7, v254
	global_load_dword v255, v254, s[18:19]
	s_mov_b64 exec, s[22:23]

.Lxb_pf_14:
	v_readlane_b32 s18, v252, 5
	s_nop 3
	s_and_b32 s18, s18, 56
	s_cmp_lg_u32 s18, 0
	s_cbranch_scc1 .Lxb_wait_14
	s_getpc_b64 s[18:19]
	s_mov_b64 s[22:23], exec
	s_mov_b64 exec, -1
	v_mbcnt_lo_u32_b32 v254, -1, 0
	v_mbcnt_hi_u32_b32 v254, -1, v254
	v_lshlrev_b32_e32 v254, 6, v254
	global_load_dword v255, v254, s[18:19]
	s_mov_b64 exec, s[22:23]
